# P0: non-temporal hint on the read-once loads (f32 weights in the transposes, x rows in the input LayerNorm)
# speedup vs baseline: 1.0143x; 1.0143x over previous
.LBB0_25:
	s_mov_b32 s15, 0
	s_lshl_b64 s[12:13], s[14:15], 2
	v_mov_b32_e32 v35, 0
	s_add_u32 s12, s22, s12
	v_add_u32_e32 v50, s4, v69
	s_addc_u32 s13, s23, s13
	v_lshlrev_b32_e32 v2, 2, v34
	v_mov_b32_e32 v3, v35
	v_lshl_add_u64 v[26:27], s[12:13], 0, v[2:3]
	v_ashrrev_i32_e32 v2, 31, v50
	v_mul_lo_u32 v4, s16, v2
	v_mul_lo_u32 v5, s17, v50
	v_mad_u64_u32 v[2:3], s[12:13], s16, v50, 0
	v_add3_u32 v3, v3, v4, v5
	v_lshl_add_u64 v[10:11], v[2:3], 2, v[26:27]
	v_add_u32_e32 v2, 2, v50
	v_ashrrev_i32_e32 v3, 31, v2
	v_mul_lo_u32 v4, s16, v3
	v_mul_lo_u32 v5, s17, v2
	v_mad_u64_u32 v[2:3], s[12:13], s16, v2, 0
	v_add3_u32 v3, v3, v4, v5
	v_lshl_add_u64 v[12:13], v[2:3], 2, v[26:27]
	v_add_u32_e32 v2, 4, v50
	v_ashrrev_i32_e32 v3, 31, v2
	v_mul_lo_u32 v4, s16, v3
	v_mul_lo_u32 v5, s17, v2
	v_mad_u64_u32 v[2:3], s[12:13], s16, v2, 0
	v_add3_u32 v3, v3, v4, v5
	v_lshl_add_u64 v[14:15], v[2:3], 2, v[26:27]
	v_add_u32_e32 v2, 6, v50
	v_ashrrev_i32_e32 v3, 31, v2
	v_mul_lo_u32 v4, s16, v3
	v_mul_lo_u32 v5, s17, v2
	v_mad_u64_u32 v[2:3], s[12:13], s16, v2, 0
	v_add3_u32 v3, v3, v4, v5
	v_lshl_add_u64 v[16:17], v[2:3], 2, v[26:27]
	v_add_u32_e32 v2, 8, v50
	v_ashrrev_i32_e32 v3, 31, v2
	v_mul_lo_u32 v4, s16, v3
	v_mul_lo_u32 v5, s17, v2
	v_mad_u64_u32 v[2:3], s[12:13], s16, v2, 0
	v_add3_u32 v3, v3, v4, v5
	v_lshl_add_u64 v[18:19], v[2:3], 2, v[26:27]
	v_add_u32_e32 v2, 10, v50
	v_ashrrev_i32_e32 v3, 31, v2
	v_mul_lo_u32 v4, s16, v3
	v_mul_lo_u32 v5, s17, v2
	v_mad_u64_u32 v[2:3], s[12:13], s16, v2, 0
	v_add3_u32 v3, v3, v4, v5
	v_lshl_add_u64 v[20:21], v[2:3], 2, v[26:27]
	v_add_u32_e32 v2, 12, v50
	v_ashrrev_i32_e32 v3, 31, v2
	v_mul_lo_u32 v4, s16, v3
	v_mul_lo_u32 v5, s17, v2
	v_mad_u64_u32 v[2:3], s[12:13], s16, v2, 0
	v_add3_u32 v3, v3, v4, v5
	v_lshl_add_u64 v[22:23], v[2:3], 2, v[26:27]
	v_add_u32_e32 v2, 14, v50
	v_ashrrev_i32_e32 v3, 31, v2
	v_mul_lo_u32 v4, s16, v3
	v_mul_lo_u32 v5, s17, v2
	v_mad_u64_u32 v[2:3], s[12:13], s16, v2, 0
	v_add3_u32 v3, v3, v4, v5
	v_lshl_add_u64 v[24:25], v[2:3], 2, v[26:27]
	global_load_dword v2, v[10:11], off nt
	global_load_dword v3, v[12:13], off nt
	global_load_dword v4, v[14:15], off nt
	global_load_dword v5, v[16:17], off nt
	global_load_dword v6, v[18:19], off nt
	global_load_dword v7, v[20:21], off nt
	global_load_dword v8, v[22:23], off nt
	global_load_dword v9, v[24:25], off nt
	v_add_u32_e32 v10, 16, v50
	v_ashrrev_i32_e32 v11, 31, v10
	v_mul_lo_u32 v12, s16, v11
	v_mul_lo_u32 v13, s17, v10
	v_mad_u64_u32 v[10:11], s[12:13], s16, v10, 0
	v_add3_u32 v11, v11, v12, v13
	v_lshl_add_u64 v[18:19], v[10:11], 2, v[26:27]
	v_add_u32_e32 v10, 18, v50
	v_ashrrev_i32_e32 v11, 31, v10
	v_mul_lo_u32 v12, s16, v11
	v_mul_lo_u32 v13, s17, v10
	v_mad_u64_u32 v[10:11], s[12:13], s16, v10, 0
	v_add3_u32 v11, v11, v12, v13
	v_lshl_add_u64 v[20:21], v[10:11], 2, v[26:27]
	v_add_u32_e32 v10, 20, v50
	v_ashrrev_i32_e32 v11, 31, v10
	v_mul_lo_u32 v12, s16, v11
	v_mul_lo_u32 v13, s17, v10
	v_mad_u64_u32 v[10:11], s[12:13], s16, v10, 0
	v_add3_u32 v11, v11, v12, v13
	v_lshl_add_u64 v[22:23], v[10:11], 2, v[26:27]
	v_add_u32_e32 v10, 22, v50
	v_ashrrev_i32_e32 v11, 31, v10
	v_mul_lo_u32 v12, s16, v11
	v_mul_lo_u32 v13, s17, v10
	v_mad_u64_u32 v[10:11], s[12:13], s16, v10, 0
	v_add3_u32 v11, v11, v12, v13
	v_lshl_add_u64 v[24:25], v[10:11], 2, v[26:27]
	v_add_u32_e32 v10, 24, v50
	v_ashrrev_i32_e32 v11, 31, v10
	v_mul_lo_u32 v12, s16, v11
	v_mul_lo_u32 v13, s17, v10
	v_mad_u64_u32 v[10:11], s[12:13], s16, v10, 0
	v_add3_u32 v11, v11, v12, v13
	v_lshl_add_u64 v[28:29], v[10:11], 2, v[26:27]
	v_add_u32_e32 v10, 26, v50
	v_ashrrev_i32_e32 v11, 31, v10
	v_mul_lo_u32 v12, s16, v11
	v_mul_lo_u32 v13, s17, v10
	v_mad_u64_u32 v[10:11], s[12:13], s16, v10, 0
	v_add3_u32 v11, v11, v12, v13
	v_lshl_add_u64 v[30:31], v[10:11], 2, v[26:27]
	v_add_u32_e32 v10, 28, v50
	v_ashrrev_i32_e32 v11, 31, v10
	v_mul_lo_u32 v12, s16, v11
	v_mul_lo_u32 v13, s17, v10
	v_mad_u64_u32 v[10:11], s[12:13], s16, v10, 0
	v_add3_u32 v11, v11, v12, v13
	v_lshl_add_u64 v[32:33], v[10:11], 2, v[26:27]
	v_add_u32_e32 v10, 30, v50
	v_ashrrev_i32_e32 v11, 31, v10
	v_mul_lo_u32 v12, s16, v11
	v_mul_lo_u32 v13, s17, v10
	v_mad_u64_u32 v[10:11], s[12:13], s16, v10, 0
	v_add3_u32 v11, v11, v12, v13
	v_lshl_add_u64 v[36:37], v[10:11], 2, v[26:27]
	global_load_dword v10, v[18:19], off nt
	global_load_dword v11, v[20:21], off nt
	global_load_dword v12, v[22:23], off nt
	global_load_dword v13, v[24:25], off nt
	global_load_dword v14, v[28:29], off nt
	global_load_dword v15, v[30:31], off nt
	global_load_dword v16, v[32:33], off nt
	global_load_dword v17, v[36:37], off nt
	v_add_u32_e32 v18, 32, v50
	v_ashrrev_i32_e32 v19, 31, v18
	v_mul_lo_u32 v20, s16, v19
	v_mul_lo_u32 v21, s17, v18
	v_mad_u64_u32 v[18:19], s[12:13], s16, v18, 0
	v_add3_u32 v19, v19, v20, v21
	v_lshl_add_u64 v[28:29], v[18:19], 2, v[26:27]
	v_add_u32_e32 v18, 34, v50
	v_ashrrev_i32_e32 v19, 31, v18
	v_mul_lo_u32 v20, s16, v19
	v_mul_lo_u32 v21, s17, v18
	v_mad_u64_u32 v[18:19], s[12:13], s16, v18, 0
	v_add3_u32 v19, v19, v20, v21
	v_lshl_add_u64 v[30:31], v[18:19], 2, v[26:27]
	v_add_u32_e32 v18, 36, v50
	v_ashrrev_i32_e32 v19, 31, v18
	v_mul_lo_u32 v20, s16, v19
	v_mul_lo_u32 v21, s17, v18
	v_mad_u64_u32 v[18:19], s[12:13], s16, v18, 0
	v_add3_u32 v19, v19, v20, v21
	v_lshl_add_u64 v[32:33], v[18:19], 2, v[26:27]
	v_add_u32_e32 v18, 38, v50
	v_ashrrev_i32_e32 v19, 31, v18
	v_mul_lo_u32 v20, s16, v19
	v_mul_lo_u32 v21, s17, v18
	v_mad_u64_u32 v[18:19], s[12:13], s16, v18, 0
	v_add3_u32 v19, v19, v20, v21
	v_lshl_add_u64 v[36:37], v[18:19], 2, v[26:27]
	v_add_u32_e32 v18, 40, v50
	v_ashrrev_i32_e32 v19, 31, v18
	v_mul_lo_u32 v20, s16, v19
	v_mul_lo_u32 v21, s17, v18
	v_mad_u64_u32 v[18:19], s[12:13], s16, v18, 0
	v_add3_u32 v19, v19, v20, v21
	v_lshl_add_u64 v[38:39], v[18:19], 2, v[26:27]
	v_add_u32_e32 v18, 42, v50
	v_ashrrev_i32_e32 v19, 31, v18
	v_mul_lo_u32 v20, s16, v19
	v_mul_lo_u32 v21, s17, v18
	v_mad_u64_u32 v[18:19], s[12:13], s16, v18, 0
	v_add3_u32 v19, v19, v20, v21
	v_lshl_add_u64 v[40:41], v[18:19], 2, v[26:27]
	v_add_u32_e32 v18, 44, v50
	v_ashrrev_i32_e32 v19, 31, v18
	v_mul_lo_u32 v20, s16, v19
	v_mul_lo_u32 v21, s17, v18
	v_mad_u64_u32 v[18:19], s[12:13], s16, v18, 0
	v_add3_u32 v19, v19, v20, v21
	v_lshl_add_u64 v[42:43], v[18:19], 2, v[26:27]
	v_add_u32_e32 v18, 46, v50
	v_ashrrev_i32_e32 v19, 31, v18
	v_mul_lo_u32 v20, s16, v19
	v_mul_lo_u32 v21, s17, v18
	v_mad_u64_u32 v[18:19], s[12:13], s16, v18, 0
	v_add3_u32 v19, v19, v20, v21
	v_lshl_add_u64 v[44:45], v[18:19], 2, v[26:27]
	global_load_dword v18, v[28:29], off nt
	global_load_dword v19, v[30:31], off nt
	global_load_dword v20, v[32:33], off nt
	global_load_dword v21, v[36:37], off nt
	global_load_dword v22, v[38:39], off nt
	global_load_dword v23, v[40:41], off nt
	global_load_dword v24, v[42:43], off nt
	global_load_dword v25, v[44:45], off nt
	v_add_u32_e32 v28, 48, v50
	v_ashrrev_i32_e32 v29, 31, v28
	v_mul_lo_u32 v30, s16, v29
	v_mul_lo_u32 v31, s17, v28
	v_mad_u64_u32 v[28:29], s[12:13], s16, v28, 0
	v_add3_u32 v29, v29, v30, v31
	v_lshl_add_u64 v[36:37], v[28:29], 2, v[26:27]
	v_add_u32_e32 v28, 50, v50
	v_ashrrev_i32_e32 v29, 31, v28
	v_mul_lo_u32 v30, s16, v29
	v_mul_lo_u32 v31, s17, v28
	v_mad_u64_u32 v[28:29], s[12:13], s16, v28, 0
	v_add3_u32 v29, v29, v30, v31
	v_lshl_add_u64 v[38:39], v[28:29], 2, v[26:27]
	v_add_u32_e32 v28, 52, v50
	v_ashrrev_i32_e32 v29, 31, v28
	v_mul_lo_u32 v30, s16, v29
	v_mul_lo_u32 v31, s17, v28
	v_mad_u64_u32 v[28:29], s[12:13], s16, v28, 0
	v_add3_u32 v29, v29, v30, v31
	v_lshl_add_u64 v[40:41], v[28:29], 2, v[26:27]
	v_add_u32_e32 v28, 54, v50
	v_ashrrev_i32_e32 v29, 31, v28
	v_mul_lo_u32 v30, s16, v29
	v_mul_lo_u32 v31, s17, v28
	v_mad_u64_u32 v[28:29], s[12:13], s16, v28, 0
	v_add3_u32 v29, v29, v30, v31
	v_lshl_add_u64 v[42:43], v[28:29], 2, v[26:27]
	v_add_u32_e32 v28, 56, v50
	v_ashrrev_i32_e32 v29, 31, v28
	v_mul_lo_u32 v30, s16, v29
	v_mul_lo_u32 v31, s17, v28
	v_mad_u64_u32 v[28:29], s[12:13], s16, v28, 0
	v_add3_u32 v29, v29, v30, v31
	v_lshl_add_u64 v[44:45], v[28:29], 2, v[26:27]
	v_add_u32_e32 v28, 58, v50
	v_ashrrev_i32_e32 v29, 31, v28
	v_mul_lo_u32 v30, s16, v29
	v_mul_lo_u32 v31, s17, v28
	v_mad_u64_u32 v[28:29], s[12:13], s16, v28, 0
	v_add3_u32 v29, v29, v30, v31
	v_lshl_add_u64 v[46:47], v[28:29], 2, v[26:27]
	v_add_u32_e32 v28, 60, v50
	v_ashrrev_i32_e32 v29, 31, v28
	v_mul_lo_u32 v30, s16, v29
	v_mul_lo_u32 v31, s17, v28
	v_mad_u64_u32 v[28:29], s[12:13], s16, v28, 0
	v_add3_u32 v29, v29, v30, v31
	v_lshl_add_u64 v[48:49], v[28:29], 2, v[26:27]
	v_add_u32_e32 v28, 62, v50
	v_ashrrev_i32_e32 v29, 31, v28
	v_mul_lo_u32 v30, s16, v29
	v_mul_lo_u32 v31, s17, v28
	v_mad_u64_u32 v[28:29], s[12:13], s16, v28, 0
	v_add3_u32 v29, v29, v30, v31
	v_lshl_add_u64 v[50:51], v[28:29], 2, v[26:27]
	global_load_dword v26, v[36:37], off nt
	global_load_dword v27, v[38:39], off nt
	global_load_dword v28, v[40:41], off nt
	global_load_dword v29, v[42:43], off nt
	global_load_dword v30, v[44:45], off nt
	global_load_dword v31, v[46:47], off nt
	global_load_dword v32, v[48:49], off nt
	global_load_dword v33, v[50:51], off nt
	v_mov_b64_e32 v[70:71], v[34:35]

.LBB0_42:
	s_mov_b32 s23, s17
	s_lshl_b64 s[12:13], s[22:23], 2
	v_add_u32_e32 v34, s20, v69
	s_add_u32 s12, s30, s12
	s_addc_u32 s13, s31, s13
	v_ashrrev_i32_e32 v36, 31, v34
	v_lshl_add_u64 v[60:61], v[70:71], 2, s[12:13]
	v_mul_lo_u32 v38, s26, v36
	v_mul_lo_u32 v39, s27, v34
	v_mad_u64_u32 v[36:37], s[12:13], s26, v34, 0
	v_add3_u32 v37, v37, v38, v39
	v_lshl_add_u64 v[44:45], v[36:37], 2, v[60:61]
	v_add_u32_e32 v36, 2, v34
	v_ashrrev_i32_e32 v37, 31, v36
	v_mul_lo_u32 v38, s26, v37
	v_mul_lo_u32 v39, s27, v36
	v_mad_u64_u32 v[36:37], s[12:13], s26, v36, 0
	v_add3_u32 v37, v37, v38, v39
	v_lshl_add_u64 v[46:47], v[36:37], 2, v[60:61]
	v_add_u32_e32 v36, 4, v34
	v_ashrrev_i32_e32 v37, 31, v36
	v_mul_lo_u32 v38, s26, v37
	v_mul_lo_u32 v39, s27, v36
	v_mad_u64_u32 v[36:37], s[12:13], s26, v36, 0
	v_add3_u32 v37, v37, v38, v39
	v_lshl_add_u64 v[48:49], v[36:37], 2, v[60:61]
	v_add_u32_e32 v36, 6, v34
	v_ashrrev_i32_e32 v37, 31, v36
	v_mul_lo_u32 v38, s26, v37
	v_mul_lo_u32 v39, s27, v36
	v_mad_u64_u32 v[36:37], s[12:13], s26, v36, 0
	v_add3_u32 v37, v37, v38, v39
	v_lshl_add_u64 v[50:51], v[36:37], 2, v[60:61]
	v_add_u32_e32 v36, 8, v34
	v_ashrrev_i32_e32 v37, 31, v36
	v_mul_lo_u32 v38, s26, v37
	v_mul_lo_u32 v39, s27, v36
	v_mad_u64_u32 v[36:37], s[12:13], s26, v36, 0
	v_add3_u32 v37, v37, v38, v39
	v_lshl_add_u64 v[52:53], v[36:37], 2, v[60:61]
	v_add_u32_e32 v36, 10, v34
	v_ashrrev_i32_e32 v37, 31, v36
	v_mul_lo_u32 v38, s26, v37
	v_mul_lo_u32 v39, s27, v36
	v_mad_u64_u32 v[36:37], s[12:13], s26, v36, 0
	v_add3_u32 v37, v37, v38, v39
	v_lshl_add_u64 v[54:55], v[36:37], 2, v[60:61]
	v_add_u32_e32 v36, 12, v34
	v_ashrrev_i32_e32 v37, 31, v36
	v_mul_lo_u32 v38, s26, v37
	v_mul_lo_u32 v39, s27, v36
	v_mad_u64_u32 v[36:37], s[12:13], s26, v36, 0
	v_add3_u32 v37, v37, v38, v39
	v_lshl_add_u64 v[56:57], v[36:37], 2, v[60:61]
	v_add_u32_e32 v36, 14, v34
	v_ashrrev_i32_e32 v37, 31, v36
	v_mul_lo_u32 v38, s26, v37
	v_mul_lo_u32 v39, s27, v36
	v_mad_u64_u32 v[36:37], s[12:13], s26, v36, 0
	v_add3_u32 v37, v37, v38, v39
	v_lshl_add_u64 v[58:59], v[36:37], 2, v[60:61]
	global_load_dword v36, v[44:45], off nt
	global_load_dword v37, v[46:47], off nt
	global_load_dword v38, v[48:49], off nt
	global_load_dword v39, v[50:51], off nt
	global_load_dword v40, v[52:53], off nt
	global_load_dword v41, v[54:55], off nt
	global_load_dword v42, v[56:57], off nt
	global_load_dword v43, v[58:59], off nt
	v_add_u32_e32 v44, 16, v34
	v_ashrrev_i32_e32 v45, 31, v44
	v_mul_lo_u32 v46, s26, v45
	v_mul_lo_u32 v47, s27, v44
	v_mad_u64_u32 v[44:45], s[12:13], s26, v44, 0
	v_add3_u32 v45, v45, v46, v47
	v_lshl_add_u64 v[52:53], v[44:45], 2, v[60:61]
	v_add_u32_e32 v44, 18, v34
	v_ashrrev_i32_e32 v45, 31, v44
	v_mul_lo_u32 v46, s26, v45
	v_mul_lo_u32 v47, s27, v44
	v_mad_u64_u32 v[44:45], s[12:13], s26, v44, 0
	v_add3_u32 v45, v45, v46, v47
	v_lshl_add_u64 v[54:55], v[44:45], 2, v[60:61]
	v_add_u32_e32 v44, 20, v34
	v_ashrrev_i32_e32 v45, 31, v44
	v_mul_lo_u32 v46, s26, v45
	v_mul_lo_u32 v47, s27, v44
	v_mad_u64_u32 v[44:45], s[12:13], s26, v44, 0
	v_add3_u32 v45, v45, v46, v47
	v_lshl_add_u64 v[56:57], v[44:45], 2, v[60:61]
	v_add_u32_e32 v44, 22, v34
	v_ashrrev_i32_e32 v45, 31, v44
	v_mul_lo_u32 v46, s26, v45
	v_mul_lo_u32 v47, s27, v44
	v_mad_u64_u32 v[44:45], s[12:13], s26, v44, 0
	v_add3_u32 v45, v45, v46, v47
	v_lshl_add_u64 v[58:59], v[44:45], 2, v[60:61]
	v_add_u32_e32 v44, 24, v34
	v_ashrrev_i32_e32 v45, 31, v44
	v_mul_lo_u32 v46, s26, v45
	v_mul_lo_u32 v47, s27, v44
	v_mad_u64_u32 v[44:45], s[12:13], s26, v44, 0
	v_add3_u32 v45, v45, v46, v47
	v_lshl_add_u64 v[62:63], v[44:45], 2, v[60:61]
	v_add_u32_e32 v44, 26, v34
	v_ashrrev_i32_e32 v45, 31, v44
	v_mul_lo_u32 v46, s26, v45
	v_mul_lo_u32 v47, s27, v44
	v_mad_u64_u32 v[44:45], s[12:13], s26, v44, 0
	v_add3_u32 v45, v45, v46, v47
	v_lshl_add_u64 v[64:65], v[44:45], 2, v[60:61]
	v_add_u32_e32 v44, 28, v34
	v_ashrrev_i32_e32 v45, 31, v44
	v_mul_lo_u32 v46, s26, v45
	v_mul_lo_u32 v47, s27, v44
	v_mad_u64_u32 v[44:45], s[12:13], s26, v44, 0
	v_add3_u32 v45, v45, v46, v47
	v_lshl_add_u64 v[66:67], v[44:45], 2, v[60:61]
	v_add_u32_e32 v44, 30, v34
	v_ashrrev_i32_e32 v45, 31, v44
	v_mul_lo_u32 v46, s26, v45
	v_mul_lo_u32 v47, s27, v44
	v_mad_u64_u32 v[44:45], s[12:13], s26, v44, 0
	v_add3_u32 v45, v45, v46, v47
	v_lshl_add_u64 v[82:83], v[44:45], 2, v[60:61]
	global_load_dword v44, v[52:53], off nt
	global_load_dword v45, v[54:55], off nt
	global_load_dword v46, v[56:57], off nt
	global_load_dword v47, v[58:59], off nt
	global_load_dword v48, v[62:63], off nt
	global_load_dword v49, v[64:65], off nt
	global_load_dword v50, v[66:67], off nt
	global_load_dword v51, v[82:83], off nt
	v_add_u32_e32 v52, 32, v34
	v_ashrrev_i32_e32 v53, 31, v52
	v_mul_lo_u32 v54, s26, v53
	v_mul_lo_u32 v55, s27, v52
	v_mad_u64_u32 v[52:53], s[12:13], s26, v52, 0
	v_add3_u32 v53, v53, v54, v55
	v_lshl_add_u64 v[62:63], v[52:53], 2, v[60:61]
	v_add_u32_e32 v52, 34, v34
	v_ashrrev_i32_e32 v53, 31, v52
	v_mul_lo_u32 v54, s26, v53
	v_mul_lo_u32 v55, s27, v52
	v_mad_u64_u32 v[52:53], s[12:13], s26, v52, 0
	v_add3_u32 v53, v53, v54, v55
	v_lshl_add_u64 v[64:65], v[52:53], 2, v[60:61]
	v_add_u32_e32 v52, 36, v34
	v_ashrrev_i32_e32 v53, 31, v52
	v_mul_lo_u32 v54, s26, v53
	v_mul_lo_u32 v55, s27, v52
	v_mad_u64_u32 v[52:53], s[12:13], s26, v52, 0
	v_add3_u32 v53, v53, v54, v55
	v_lshl_add_u64 v[66:67], v[52:53], 2, v[60:61]
	v_add_u32_e32 v52, 38, v34
	v_ashrrev_i32_e32 v53, 31, v52
	v_mul_lo_u32 v54, s26, v53
	v_mul_lo_u32 v55, s27, v52
	v_mad_u64_u32 v[52:53], s[12:13], s26, v52, 0
	v_add3_u32 v53, v53, v54, v55
	v_lshl_add_u64 v[82:83], v[52:53], 2, v[60:61]
	v_add_u32_e32 v52, 40, v34
	v_ashrrev_i32_e32 v53, 31, v52
	v_mul_lo_u32 v54, s26, v53
	v_mul_lo_u32 v55, s27, v52
	v_mad_u64_u32 v[52:53], s[12:13], s26, v52, 0
	v_add3_u32 v53, v53, v54, v55
	v_lshl_add_u64 v[84:85], v[52:53], 2, v[60:61]
	v_add_u32_e32 v52, 42, v34
	v_ashrrev_i32_e32 v53, 31, v52
	v_mul_lo_u32 v54, s26, v53
	v_mul_lo_u32 v55, s27, v52
	v_mad_u64_u32 v[52:53], s[12:13], s26, v52, 0
	v_add3_u32 v53, v53, v54, v55
	v_lshl_add_u64 v[86:87], v[52:53], 2, v[60:61]
	v_add_u32_e32 v52, 44, v34
	v_ashrrev_i32_e32 v53, 31, v52
	v_mul_lo_u32 v54, s26, v53
	v_mul_lo_u32 v55, s27, v52
	v_mad_u64_u32 v[52:53], s[12:13], s26, v52, 0
	v_add3_u32 v53, v53, v54, v55
	v_lshl_add_u64 v[88:89], v[52:53], 2, v[60:61]
	v_add_u32_e32 v52, 46, v34
	v_ashrrev_i32_e32 v53, 31, v52
	v_mul_lo_u32 v54, s26, v53
	v_mul_lo_u32 v55, s27, v52
	v_mad_u64_u32 v[52:53], s[12:13], s26, v52, 0
	v_add3_u32 v53, v53, v54, v55
	v_lshl_add_u64 v[90:91], v[52:53], 2, v[60:61]
	global_load_dword v52, v[62:63], off nt
	global_load_dword v53, v[64:65], off nt
	global_load_dword v54, v[66:67], off nt
	global_load_dword v55, v[82:83], off nt
	global_load_dword v56, v[84:85], off nt
	global_load_dword v57, v[86:87], off nt
	global_load_dword v58, v[88:89], off nt
	global_load_dword v59, v[90:91], off nt
	v_add_u32_e32 v62, 48, v34
	v_ashrrev_i32_e32 v63, 31, v62
	v_mul_lo_u32 v64, s26, v63
	v_mul_lo_u32 v65, s27, v62
	v_mad_u64_u32 v[62:63], s[12:13], s26, v62, 0
	v_add3_u32 v63, v63, v64, v65
	v_lshl_add_u64 v[82:83], v[62:63], 2, v[60:61]
	v_add_u32_e32 v62, 50, v34
	v_ashrrev_i32_e32 v63, 31, v62
	v_mul_lo_u32 v64, s26, v63
	v_mul_lo_u32 v65, s27, v62
	v_mad_u64_u32 v[62:63], s[12:13], s26, v62, 0
	v_add3_u32 v63, v63, v64, v65
	v_lshl_add_u64 v[84:85], v[62:63], 2, v[60:61]
	v_add_u32_e32 v62, 52, v34
	v_ashrrev_i32_e32 v63, 31, v62
	v_mul_lo_u32 v64, s26, v63
	v_mul_lo_u32 v65, s27, v62
	v_mad_u64_u32 v[62:63], s[12:13], s26, v62, 0
	v_add3_u32 v63, v63, v64, v65
	v_lshl_add_u64 v[86:87], v[62:63], 2, v[60:61]
	v_add_u32_e32 v62, 54, v34
	v_ashrrev_i32_e32 v63, 31, v62
	v_mul_lo_u32 v64, s26, v63
	v_mul_lo_u32 v65, s27, v62
	v_mad_u64_u32 v[62:63], s[12:13], s26, v62, 0
	v_add3_u32 v63, v63, v64, v65
	v_lshl_add_u64 v[88:89], v[62:63], 2, v[60:61]
	v_add_u32_e32 v62, 56, v34
	v_ashrrev_i32_e32 v63, 31, v62
	v_mul_lo_u32 v64, s26, v63
	v_mul_lo_u32 v65, s27, v62
	v_mad_u64_u32 v[62:63], s[12:13], s26, v62, 0
	v_add3_u32 v63, v63, v64, v65
	v_lshl_add_u64 v[90:91], v[62:63], 2, v[60:61]
	v_add_u32_e32 v62, 58, v34
	v_ashrrev_i32_e32 v63, 31, v62
	v_mul_lo_u32 v64, s26, v63
	v_mul_lo_u32 v65, s27, v62
	v_mad_u64_u32 v[62:63], s[12:13], s26, v62, 0
	v_add3_u32 v63, v63, v64, v65
	v_lshl_add_u64 v[92:93], v[62:63], 2, v[60:61]
	v_add_u32_e32 v62, 60, v34
	v_ashrrev_i32_e32 v63, 31, v62
	v_mul_lo_u32 v64, s26, v63
	v_mul_lo_u32 v65, s27, v62
	v_mad_u64_u32 v[62:63], s[12:13], s26, v62, 0
	v_add3_u32 v63, v63, v64, v65
	v_add_u32_e32 v34, 62, v34
	v_lshl_add_u64 v[94:95], v[62:63], 2, v[60:61]
	v_ashrrev_i32_e32 v62, 31, v34
	v_mul_lo_u32 v64, s26, v62
	v_mul_lo_u32 v65, s27, v34
	v_mad_u64_u32 v[62:63], s[12:13], s26, v34, 0
	v_add3_u32 v63, v63, v64, v65
	v_lshl_add_u64 v[96:97], v[62:63], 2, v[60:61]
	global_load_dword v60, v[82:83], off nt
	global_load_dword v61, v[84:85], off nt
	global_load_dword v62, v[86:87], off nt
	global_load_dword v63, v[88:89], off nt
	global_load_dword v64, v[90:91], off nt
	global_load_dword v65, v[92:93], off nt
	global_load_dword v66, v[94:95], off nt
	global_load_dword v67, v[96:97], off nt

.LBB0_58:
	s_mov_b32 s15, s17
	s_lshl_b64 s[12:13], s[14:15], 2
	v_add_u32_e32 v89, s4, v69
	s_add_u32 s12, s34, s12
	s_addc_u32 s13, s35, s13
	v_ashrrev_i32_e32 v2, 31, v89
	v_lshl_add_u64 v[26:27], v[70:71], 2, s[12:13]
	v_mul_lo_u32 v4, s28, v2
	v_mul_lo_u32 v5, s29, v89
	v_mad_u64_u32 v[2:3], s[12:13], s28, v89, 0
	v_add3_u32 v3, v3, v4, v5
	v_lshl_add_u64 v[10:11], v[2:3], 2, v[26:27]
	v_add_u32_e32 v2, 2, v89
	v_ashrrev_i32_e32 v3, 31, v2
	v_mul_lo_u32 v4, s28, v3
	v_mul_lo_u32 v5, s29, v2
	v_mad_u64_u32 v[2:3], s[12:13], s28, v2, 0
	v_add3_u32 v3, v3, v4, v5
	v_lshl_add_u64 v[12:13], v[2:3], 2, v[26:27]
	v_add_u32_e32 v2, 4, v89
	v_ashrrev_i32_e32 v3, 31, v2
	v_mul_lo_u32 v4, s28, v3
	v_mul_lo_u32 v5, s29, v2
	v_mad_u64_u32 v[2:3], s[12:13], s28, v2, 0
	v_add3_u32 v3, v3, v4, v5
	v_lshl_add_u64 v[14:15], v[2:3], 2, v[26:27]
	v_add_u32_e32 v2, 6, v89
	v_ashrrev_i32_e32 v3, 31, v2
	v_mul_lo_u32 v4, s28, v3
	v_mul_lo_u32 v5, s29, v2
	v_mad_u64_u32 v[2:3], s[12:13], s28, v2, 0
	v_add3_u32 v3, v3, v4, v5
	v_lshl_add_u64 v[16:17], v[2:3], 2, v[26:27]
	v_add_u32_e32 v2, 8, v89
	v_ashrrev_i32_e32 v3, 31, v2
	v_mul_lo_u32 v4, s28, v3
	v_mul_lo_u32 v5, s29, v2
	v_mad_u64_u32 v[2:3], s[12:13], s28, v2, 0
	v_add3_u32 v3, v3, v4, v5
	v_lshl_add_u64 v[18:19], v[2:3], 2, v[26:27]
	v_add_u32_e32 v2, 10, v89
	v_ashrrev_i32_e32 v3, 31, v2
	v_mul_lo_u32 v4, s28, v3
	v_mul_lo_u32 v5, s29, v2
	v_mad_u64_u32 v[2:3], s[12:13], s28, v2, 0
	v_add3_u32 v3, v3, v4, v5
	v_lshl_add_u64 v[20:21], v[2:3], 2, v[26:27]
	v_add_u32_e32 v2, 12, v89
	v_ashrrev_i32_e32 v3, 31, v2
	v_mul_lo_u32 v4, s28, v3
	v_mul_lo_u32 v5, s29, v2
	v_mad_u64_u32 v[2:3], s[12:13], s28, v2, 0
	v_add3_u32 v3, v3, v4, v5
	v_lshl_add_u64 v[22:23], v[2:3], 2, v[26:27]
	v_add_u32_e32 v2, 14, v89
	v_ashrrev_i32_e32 v3, 31, v2
	v_mul_lo_u32 v4, s28, v3
	v_mul_lo_u32 v5, s29, v2
	v_mad_u64_u32 v[2:3], s[12:13], s28, v2, 0
	v_add3_u32 v3, v3, v4, v5
	v_lshl_add_u64 v[24:25], v[2:3], 2, v[26:27]
	global_load_dword v2, v[10:11], off nt
	global_load_dword v3, v[12:13], off nt
	global_load_dword v4, v[14:15], off nt
	global_load_dword v5, v[16:17], off nt
	global_load_dword v6, v[18:19], off nt
	global_load_dword v7, v[20:21], off nt
	global_load_dword v8, v[22:23], off nt
	global_load_dword v9, v[24:25], off nt
	v_add_u32_e32 v10, 16, v89
	v_ashrrev_i32_e32 v11, 31, v10
	v_mul_lo_u32 v12, s28, v11
	v_mul_lo_u32 v13, s29, v10
	v_mad_u64_u32 v[10:11], s[12:13], s28, v10, 0
	v_add3_u32 v11, v11, v12, v13
	v_lshl_add_u64 v[18:19], v[10:11], 2, v[26:27]
	v_add_u32_e32 v10, 18, v89
	v_ashrrev_i32_e32 v11, 31, v10
	v_mul_lo_u32 v12, s28, v11
	v_mul_lo_u32 v13, s29, v10
	v_mad_u64_u32 v[10:11], s[12:13], s28, v10, 0
	v_add3_u32 v11, v11, v12, v13
	v_lshl_add_u64 v[20:21], v[10:11], 2, v[26:27]
	v_add_u32_e32 v10, 20, v89
	v_ashrrev_i32_e32 v11, 31, v10
	v_mul_lo_u32 v12, s28, v11
	v_mul_lo_u32 v13, s29, v10
	v_mad_u64_u32 v[10:11], s[12:13], s28, v10, 0
	v_add3_u32 v11, v11, v12, v13
	v_lshl_add_u64 v[22:23], v[10:11], 2, v[26:27]
	v_add_u32_e32 v10, 22, v89
	v_ashrrev_i32_e32 v11, 31, v10
	v_mul_lo_u32 v12, s28, v11
	v_mul_lo_u32 v13, s29, v10
	v_mad_u64_u32 v[10:11], s[12:13], s28, v10, 0
	v_add3_u32 v11, v11, v12, v13
	v_lshl_add_u64 v[24:25], v[10:11], 2, v[26:27]
	v_add_u32_e32 v10, 24, v89
	v_ashrrev_i32_e32 v11, 31, v10
	v_mul_lo_u32 v12, s28, v11
	v_mul_lo_u32 v13, s29, v10
	v_mad_u64_u32 v[10:11], s[12:13], s28, v10, 0
	v_add3_u32 v11, v11, v12, v13
	v_lshl_add_u64 v[28:29], v[10:11], 2, v[26:27]
	v_add_u32_e32 v10, 26, v89
	v_ashrrev_i32_e32 v11, 31, v10
	v_mul_lo_u32 v12, s28, v11
	v_mul_lo_u32 v13, s29, v10
	v_mad_u64_u32 v[10:11], s[12:13], s28, v10, 0
	v_add3_u32 v11, v11, v12, v13
	v_lshl_add_u64 v[30:31], v[10:11], 2, v[26:27]
	v_add_u32_e32 v10, 28, v89
	v_ashrrev_i32_e32 v11, 31, v10
	v_mul_lo_u32 v12, s28, v11
	v_mul_lo_u32 v13, s29, v10
	v_mad_u64_u32 v[10:11], s[12:13], s28, v10, 0
	v_add3_u32 v11, v11, v12, v13
	v_lshl_add_u64 v[32:33], v[10:11], 2, v[26:27]
	v_add_u32_e32 v10, 30, v89
	v_ashrrev_i32_e32 v11, 31, v10
	v_mul_lo_u32 v12, s28, v11
	v_mul_lo_u32 v13, s29, v10
	v_mad_u64_u32 v[10:11], s[12:13], s28, v10, 0
	v_add3_u32 v11, v11, v12, v13
	v_lshl_add_u64 v[90:91], v[10:11], 2, v[26:27]
	global_load_dword v10, v[18:19], off nt
	global_load_dword v11, v[20:21], off nt
	global_load_dword v12, v[22:23], off nt
	global_load_dword v13, v[24:25], off nt
	global_load_dword v14, v[28:29], off nt
	global_load_dword v15, v[30:31], off nt
	global_load_dword v16, v[32:33], off nt
	global_load_dword v17, v[90:91], off nt
	v_add_u32_e32 v18, 32, v89
	v_ashrrev_i32_e32 v19, 31, v18
	v_mul_lo_u32 v20, s28, v19
	v_mul_lo_u32 v21, s29, v18
	v_mad_u64_u32 v[18:19], s[12:13], s28, v18, 0
	v_add3_u32 v19, v19, v20, v21
	v_lshl_add_u64 v[28:29], v[18:19], 2, v[26:27]
	v_add_u32_e32 v18, 34, v89
	v_ashrrev_i32_e32 v19, 31, v18
	v_mul_lo_u32 v20, s28, v19
	v_mul_lo_u32 v21, s29, v18
	v_mad_u64_u32 v[18:19], s[12:13], s28, v18, 0
	v_add3_u32 v19, v19, v20, v21
	v_lshl_add_u64 v[30:31], v[18:19], 2, v[26:27]
	v_add_u32_e32 v18, 36, v89
	v_ashrrev_i32_e32 v19, 31, v18
	v_mul_lo_u32 v20, s28, v19
	v_mul_lo_u32 v21, s29, v18
	v_mad_u64_u32 v[18:19], s[12:13], s28, v18, 0
	v_add3_u32 v19, v19, v20, v21
	v_lshl_add_u64 v[32:33], v[18:19], 2, v[26:27]
	v_add_u32_e32 v18, 38, v89
	v_ashrrev_i32_e32 v19, 31, v18
	v_mul_lo_u32 v20, s28, v19
	v_mul_lo_u32 v21, s29, v18
	v_mad_u64_u32 v[18:19], s[12:13], s28, v18, 0
	v_add3_u32 v19, v19, v20, v21
	v_lshl_add_u64 v[90:91], v[18:19], 2, v[26:27]
	v_add_u32_e32 v18, 40, v89
	v_ashrrev_i32_e32 v19, 31, v18
	v_mul_lo_u32 v20, s28, v19
	v_mul_lo_u32 v21, s29, v18
	v_mad_u64_u32 v[18:19], s[12:13], s28, v18, 0
	v_add3_u32 v19, v19, v20, v21
	v_lshl_add_u64 v[92:93], v[18:19], 2, v[26:27]
	v_add_u32_e32 v18, 42, v89
	v_ashrrev_i32_e32 v19, 31, v18
	v_mul_lo_u32 v20, s28, v19
	v_mul_lo_u32 v21, s29, v18
	v_mad_u64_u32 v[18:19], s[12:13], s28, v18, 0
	v_add3_u32 v19, v19, v20, v21
	v_lshl_add_u64 v[94:95], v[18:19], 2, v[26:27]
	v_add_u32_e32 v18, 44, v89
	v_ashrrev_i32_e32 v19, 31, v18
	v_mul_lo_u32 v20, s28, v19
	v_mul_lo_u32 v21, s29, v18
	v_mad_u64_u32 v[18:19], s[12:13], s28, v18, 0
	v_add3_u32 v19, v19, v20, v21
	v_lshl_add_u64 v[96:97], v[18:19], 2, v[26:27]
	v_add_u32_e32 v18, 46, v89
	v_ashrrev_i32_e32 v19, 31, v18
	v_mul_lo_u32 v20, s28, v19
	v_mul_lo_u32 v21, s29, v18
	v_mad_u64_u32 v[18:19], s[12:13], s28, v18, 0
	v_add3_u32 v19, v19, v20, v21
	v_lshl_add_u64 v[98:99], v[18:19], 2, v[26:27]
	global_load_dword v18, v[28:29], off nt
	global_load_dword v19, v[30:31], off nt
	global_load_dword v20, v[32:33], off nt
	global_load_dword v21, v[90:91], off nt
	global_load_dword v22, v[92:93], off nt
	global_load_dword v23, v[94:95], off nt
	global_load_dword v24, v[96:97], off nt
	global_load_dword v25, v[98:99], off nt
	v_add_u32_e32 v28, 48, v89
	v_ashrrev_i32_e32 v29, 31, v28
	v_mul_lo_u32 v30, s28, v29
	v_mul_lo_u32 v31, s29, v28
	v_mad_u64_u32 v[28:29], s[12:13], s28, v28, 0
	v_add3_u32 v29, v29, v30, v31
	v_lshl_add_u64 v[90:91], v[28:29], 2, v[26:27]
	v_add_u32_e32 v28, 50, v89
	v_ashrrev_i32_e32 v29, 31, v28
	v_mul_lo_u32 v30, s28, v29
	v_mul_lo_u32 v31, s29, v28
	v_mad_u64_u32 v[28:29], s[12:13], s28, v28, 0
	v_add3_u32 v29, v29, v30, v31
	v_lshl_add_u64 v[92:93], v[28:29], 2, v[26:27]
	v_add_u32_e32 v28, 52, v89
	v_ashrrev_i32_e32 v29, 31, v28
	v_mul_lo_u32 v30, s28, v29
	v_mul_lo_u32 v31, s29, v28
	v_mad_u64_u32 v[28:29], s[12:13], s28, v28, 0
	v_add3_u32 v29, v29, v30, v31
	v_lshl_add_u64 v[94:95], v[28:29], 2, v[26:27]
	v_add_u32_e32 v28, 54, v89
	v_ashrrev_i32_e32 v29, 31, v28
	v_mul_lo_u32 v30, s28, v29
	v_mul_lo_u32 v31, s29, v28
	v_mad_u64_u32 v[28:29], s[12:13], s28, v28, 0
	v_add3_u32 v29, v29, v30, v31
	v_lshl_add_u64 v[96:97], v[28:29], 2, v[26:27]
	v_add_u32_e32 v28, 56, v89
	v_ashrrev_i32_e32 v29, 31, v28
	v_mul_lo_u32 v30, s28, v29
	v_mul_lo_u32 v31, s29, v28
	v_mad_u64_u32 v[28:29], s[12:13], s28, v28, 0
	v_add3_u32 v29, v29, v30, v31
	v_lshl_add_u64 v[98:99], v[28:29], 2, v[26:27]
	v_add_u32_e32 v28, 58, v89
	v_ashrrev_i32_e32 v29, 31, v28
	v_mul_lo_u32 v30, s28, v29
	v_mul_lo_u32 v31, s29, v28
	v_mad_u64_u32 v[28:29], s[12:13], s28, v28, 0
	v_add3_u32 v29, v29, v30, v31
	v_lshl_add_u64 v[100:101], v[28:29], 2, v[26:27]
	v_add_u32_e32 v28, 60, v89
	v_ashrrev_i32_e32 v29, 31, v28
	v_mul_lo_u32 v30, s28, v29
	v_mul_lo_u32 v31, s29, v28
	v_mad_u64_u32 v[28:29], s[12:13], s28, v28, 0
	v_add3_u32 v29, v29, v30, v31
	v_lshl_add_u64 v[102:103], v[28:29], 2, v[26:27]
	v_add_u32_e32 v28, 62, v89
	v_ashrrev_i32_e32 v29, 31, v28
	v_mul_lo_u32 v30, s28, v29
	v_mul_lo_u32 v31, s29, v28
	v_mad_u64_u32 v[28:29], s[12:13], s28, v28, 0
	v_add3_u32 v29, v29, v30, v31
	v_lshl_add_u64 v[104:105], v[28:29], 2, v[26:27]
	global_load_dword v26, v[90:91], off nt
	global_load_dword v27, v[92:93], off nt
	global_load_dword v28, v[94:95], off nt
	global_load_dword v29, v[96:97], off nt
	global_load_dword v30, v[98:99], off nt
	global_load_dword v31, v[100:101], off nt
	global_load_dword v32, v[102:103], off nt
	global_load_dword v33, v[104:105], off nt

.LBB0_81:
	s_mov_b64 s[4:5], s[98:99]
	s_add_i32 s16, s14, 0xffe00000
	s_mov_b64 s[6:7], s[98:99]
	s_lshl_b64 s[34:35], s[16:17], 2
	s_add_u32 s4, s4, s34
	s_mov_b32 s15, s17
	s_addc_u32 s5, s5, s35
	s_lshl_b64 s[34:35], s[14:15], 2
	v_lshl_add_u64 v[34:35], s[4:5], 0, v[66:67]
	s_add_u32 s4, s6, s34
	global_load_dwordx4 v[62:65], v[34:35], off nt
	global_load_dwordx4 v[58:61], v[34:35], off offset:1024 nt
	global_load_dwordx4 v[50:53], v[34:35], off offset:2048 nt
	global_load_dwordx4 v[54:57], v[34:35], off offset:3072 nt
	s_addc_u32 s5, s7, s35
	v_lshl_add_u64 v[70:71], s[4:5], 0, v[66:67]
	global_load_dwordx4 v[46:49], v[70:71], off nt
	global_load_dwordx4 v[42:45], v[70:71], off offset:1024 nt
	global_load_dwordx4 v[38:41], v[70:71], off offset:2048 nt
	global_load_dwordx4 v[34:37], v[70:71], off offset:3072 nt
	s_mov_b64 s[36:37], s[0:1]
	s_load_dwordx2 s[4:5], s[36:37], 0x80
	s_lshl_b64 s[34:35], s[16:17], 1
	s_mov_b64 s[18:19], s[0:1]
	s_mov_b64 s[20:21], s[0:1]
	s_mov_b64 s[22:23], s[0:1]
	s_waitcnt lgkmcnt(0)
	s_add_u32 s4, s4, s34
	s_addc_u32 s5, s5, s35
	v_lshl_add_u64 v[70:71], s[4:5], 0, v[68:69]
	v_add_co_u32_e32 v70, vcc, s39, v70
	s_lshl_b64 s[36:37], s[14:15], 1
	s_nop 0
	v_addc_co_u32_e32 v71, vcc, 0, v71, vcc
	s_mov_b64 s[24:25], s[0:1]
	s_mov_b64 s[26:27], s[0:1]
	s_mov_b64 s[28:29], s[0:1]
	s_mov_b64 s[30:31], s[0:1]
	s_waitcnt vmcnt(7)
	v_mov_b32_e32 v74, v63
	v_mov_b32_e32 v75, v64
	v_mov_b32_e32 v76, v62
	v_mov_b32_e32 v77, v65
	s_waitcnt vmcnt(6)
	v_mov_b32_e32 v78, v59
	v_mov_b32_e32 v79, v60
	v_mov_b32_e32 v80, v58
	v_mov_b32_e32 v81, v61
	s_waitcnt vmcnt(5)
	v_add_f32_e32 v82, v50, v51
	v_add_f32_e32 v84, v52, v53
	s_waitcnt vmcnt(4)
	v_mov_b32_e32 v83, v56
	v_mov_b32_e32 v85, v57
	v_pk_add_f32 v[74:75], v[74:75], v[76:77]
	v_pk_add_f32 v[76:77], v[78:79], v[80:81]
	v_pk_add_f32 v[78:79], v[82:83], v[84:85]
	v_add_f32_e32 v86, v74, v75
	s_waitcnt vmcnt(3)
	v_mov_b32_e32 v74, v47
	v_mov_b32_e32 v75, v48
	v_mov_b32_e32 v80, v46
	v_mov_b32_e32 v81, v49
	v_pk_add_f32 v[76:77], v[76:77], v[76:77] op_sel:[0,1] op_sel_hi:[1,0]
	s_waitcnt vmcnt(2)
	v_mov_b32_e32 v82, v43
	v_mov_b32_e32 v83, v44
	v_mov_b32_e32 v84, v42
	v_mov_b32_e32 v85, v45
	v_mov_b32_e32 v87, v54
	v_add_f32_e32 v86, 0, v86
	v_pk_add_f32 v[74:75], v[74:75], v[80:81]
	v_pk_add_f32 v[80:81], v[82:83], v[84:85]
	v_mov_b32_e32 v77, v55
	v_add_f32_e32 v84, v74, v75
	v_pk_add_f32 v[74:75], v[80:81], v[80:81] op_sel:[0,1] op_sel_hi:[1,0]
	v_pk_add_f32 v[76:77], v[86:87], v[76:77]
	s_waitcnt vmcnt(1)
	v_add_f32_e32 v88, v38, v39
	v_add_f32_e32 v90, v40, v41
	s_waitcnt vmcnt(0)
	v_mov_b32_e32 v93, v34
	v_mov_b32_e32 v89, v36
	v_mov_b32_e32 v91, v37
	v_add_f32_e32 v92, 0, v84
	v_pk_add_f32 v[76:77], v[76:77], v[78:79]
	v_mov_b32_e32 v75, v35
	v_pk_add_f32 v[82:83], v[88:89], v[90:91]
	v_add_f32_e32 v76, v76, v77
	v_pk_add_f32 v[74:75], v[92:93], v[74:75]
	v_pk_add_f32 v[74:75], v[74:75], v[82:83]
	s_nop 0
	v_add_f32_e32 v74, v74, v75
	s_nop 1
	v_add_f32_dpp v76, v76, v76 quad_perm:[1,0,3,2] row_mask:0xf bank_mask:0xf
	v_add_f32_dpp v74, v74, v74 quad_perm:[1,0,3,2] row_mask:0xf bank_mask:0xf
	s_nop 1
	v_add_f32_dpp v76, v76, v76 quad_perm:[2,3,0,1] row_mask:0xf bank_mask:0xf
	v_add_f32_dpp v74, v74, v74 quad_perm:[2,3,0,1] row_mask:0xf bank_mask:0xf
	s_nop 1
	v_add_f32_dpp v76, v76, v76 row_ror:4 row_mask:0xf bank_mask:0xf
	v_add_f32_dpp v74, v74, v74 row_ror:4 row_mask:0xf bank_mask:0xf
	s_nop 1
	v_add_f32_dpp v76, v76, v76 row_ror:8 row_mask:0xf bank_mask:0xf
	v_add_f32_dpp v74, v74, v74 row_ror:8 row_mask:0xf bank_mask:0xf
	s_nop 1
	v_mov_b32_e32 v77, v76
	v_mov_b32_e32 v75, v74
	s_nop 1
	v_permlane16_swap_b32_e32 v77, v76
	v_permlane16_swap_b32_e32 v75, v74
	s_nop 1
	v_add_f32_e32 v76, v77, v76
	v_add_f32_e32 v74, v75, v74
	v_mov_b32_e32 v77, v76
	v_mov_b32_e32 v75, v74
	s_nop 1
	v_permlane32_swap_b32_e32 v77, v76
	v_permlane32_swap_b32_e32 v75, v74
	s_nop 1
	v_add_f32_e32 v76, v77, v76
	v_add_f32_e32 v74, v75, v74
	v_fmamk_f32 v63, v76, 0xba800000, v63
	v_fmamk_f32 v62, v76, 0xba800000, v62
	v_fmamk_f32 v65, v76, 0xba800000, v65
	v_fmac_f32_e32 v64, 0xba800000, v76
	v_fmamk_f32 v59, v76, 0xba800000, v59
	v_fmamk_f32 v58, v76, 0xba800000, v58
	v_fmamk_f32 v61, v76, 0xba800000, v61
	v_fmac_f32_e32 v60, 0xba800000, v76
	v_fmamk_f32 v51, v76, 0xba800000, v51
	v_fmamk_f32 v50, v76, 0xba800000, v50
	v_fmamk_f32 v53, v76, 0xba800000, v53
	v_fmac_f32_e32 v52, 0xba800000, v76
	v_fmamk_f32 v57, v76, 0xba800000, v57
	v_fmamk_f32 v56, v76, 0xba800000, v56
	v_fmamk_f32 v55, v76, 0xba800000, v55
	v_fmac_f32_e32 v54, 0xba800000, v76
	v_mov_b32_e32 v83, v74
	v_pk_mul_f32 v[74:75], v[64:65], v[64:65]
	v_pk_mul_f32 v[76:77], v[62:63], v[62:63]
	v_pk_mul_f32 v[78:79], v[60:61], v[60:61]
	v_pk_mul_f32 v[80:81], v[58:59], v[58:59]
	v_pk_mov_b32 v[86:87], v[76:77], v[74:75] op_sel:[1,0]
	v_mov_b32_e32 v77, v75
	v_pk_mov_b32 v[74:75], v[80:81], v[78:79] op_sel:[1,0]
	v_mov_b32_e32 v81, v79
	v_mul_f32_e32 v82, v51, v51
	v_mul_f32_e32 v84, v53, v53
	v_fmamk_f32 v47, v83, 0xba800000, v47
	v_fmamk_f32 v46, v83, 0xba800000, v46
	v_fmamk_f32 v49, v83, 0xba800000, v49
	v_fmac_f32_e32 v48, 0xba800000, v83
	v_fmamk_f32 v43, v83, 0xba800000, v43
	v_fmamk_f32 v42, v83, 0xba800000, v42
	v_fmamk_f32 v45, v83, 0xba800000, v45
	v_fmac_f32_e32 v44, 0xba800000, v83
	v_pk_add_f32 v[76:77], v[86:87], v[76:77]
	v_pk_add_f32 v[74:75], v[74:75], v[80:81]
	v_mul_f32_e32 v91, v54, v54
	v_mul_f32_e32 v93, v55, v55
	v_mul_f32_e32 v90, v56, v56
	v_mul_f32_e32 v92, v57, v57
	v_fmamk_f32 v39, v83, 0xba800000, v39
	v_fmamk_f32 v38, v83, 0xba800000, v38
	v_fmamk_f32 v41, v83, 0xba800000, v41
	v_fmac_f32_e32 v40, 0xba800000, v83
	v_fmamk_f32 v37, v83, 0xba800000, v37
	v_fmamk_f32 v36, v83, 0xba800000, v36
	v_fmamk_f32 v35, v83, 0xba800000, v35
	v_fmac_f32_e32 v34, 0xba800000, v83
	v_pk_fma_f32 v[78:79], v[50:51], v[50:51], v[82:83] op_sel_hi:[1,1,0]
	v_pk_fma_f32 v[82:83], v[52:53], v[52:53], v[84:85] op_sel_hi:[1,1,0]
	v_pk_mul_f32 v[84:85], v[48:49], v[48:49]
	v_pk_mul_f32 v[86:87], v[46:47], v[46:47]
	v_pk_mul_f32 v[80:81], v[44:45], v[44:45]
	v_pk_mul_f32 v[88:89], v[42:43], v[42:43]
	v_pk_add_f32 v[76:77], v[76:77], v[76:77] op_sel:[0,1] op_sel_hi:[1,0]
	v_pk_add_f32 v[74:75], v[74:75], v[74:75] op_sel:[0,1] op_sel_hi:[1,0]
	v_mov_b32_e32 v79, v90
	v_mov_b32_e32 v83, v92
	v_pk_mov_b32 v[94:95], v[86:87], v[84:85] op_sel:[1,0]
	v_mov_b32_e32 v87, v85
	v_pk_mov_b32 v[84:85], v[88:89], v[80:81] op_sel:[1,0]
	v_mov_b32_e32 v89, v81
	v_mov_b32_e32 v77, v91
	v_mov_b32_e32 v75, v93
	v_mul_f32_e32 v90, v39, v39
	v_mul_f32_e32 v92, v41, v41
	v_pk_add_f32 v[78:79], v[78:79], v[82:83]
	v_pk_add_f32 v[86:87], v[94:95], v[86:87]
	v_pk_add_f32 v[84:85], v[84:85], v[88:89]
	v_pk_add_f32 v[74:75], v[76:77], v[74:75]
	v_mul_f32_e32 v96, v34, v34
	v_mul_f32_e32 v97, v35, v35
	v_mul_f32_e32 v98, v36, v36
	v_mul_f32_e32 v99, v37, v37
	v_pk_fma_f32 v[80:81], v[38:39], v[38:39], v[90:91] op_sel_hi:[1,1,0]
	v_pk_fma_f32 v[82:83], v[40:41], v[40:41], v[92:93] op_sel_hi:[1,1,0]
	v_pk_add_f32 v[76:77], v[86:87], v[86:87] op_sel:[0,1] op_sel_hi:[1,0]
	v_pk_add_f32 v[84:85], v[84:85], v[84:85] op_sel:[0,1] op_sel_hi:[1,0]
	v_pk_add_f32 v[74:75], v[74:75], v[78:79]
	v_mov_b32_e32 v81, v98
	v_mov_b32_e32 v83, v99
	v_mov_b32_e32 v77, v96
	v_mov_b32_e32 v85, v97
	v_add_f32_e32 v78, v74, v75
	v_pk_add_f32 v[80:81], v[80:81], v[82:83]
	v_pk_add_f32 v[74:75], v[76:77], v[84:85]
	v_pk_add_f32 v[74:75], v[74:75], v[80:81]
	v_mov_b32_e32 v76, v78
	s_nop 0
	v_add_f32_e32 v74, v74, v75
	s_nop 1
	v_add_f32_dpp v76, v76, v76 quad_perm:[1,0,3,2] row_mask:0xf bank_mask:0xf
	v_add_f32_dpp v74, v74, v74 quad_perm:[1,0,3,2] row_mask:0xf bank_mask:0xf
	s_nop 1
	v_add_f32_dpp v76, v76, v76 quad_perm:[2,3,0,1] row_mask:0xf bank_mask:0xf
	v_add_f32_dpp v74, v74, v74 quad_perm:[2,3,0,1] row_mask:0xf bank_mask:0xf
	s_nop 1
	v_add_f32_dpp v76, v76, v76 row_ror:4 row_mask:0xf bank_mask:0xf
	v_add_f32_dpp v74, v74, v74 row_ror:4 row_mask:0xf bank_mask:0xf
	s_nop 1
	v_add_f32_dpp v76, v76, v76 row_ror:8 row_mask:0xf bank_mask:0xf
	v_add_f32_dpp v74, v74, v74 row_ror:8 row_mask:0xf bank_mask:0xf
	s_nop 1
	v_mov_b32_e32 v77, v76
	v_mov_b32_e32 v75, v74
	s_nop 1
	v_permlane16_swap_b32_e32 v77, v76
	v_permlane16_swap_b32_e32 v75, v74
	s_nop 1
	v_add_f32_e32 v76, v77, v76
	v_add_f32_e32 v74, v75, v74
	v_mov_b32_e32 v77, v76
	v_mov_b32_e32 v75, v74
	s_nop 1
	v_permlane32_swap_b32_e32 v77, v76
	v_permlane32_swap_b32_e32 v75, v74
	s_nop 1
	v_add_f32_e32 v76, v77, v76
	v_add_f32_e32 v74, v75, v74
	v_fmamk_f32 v76, v76, 0x3a800000, v72
	v_mul_f32_e32 v77, 0x4f800000, v76
	v_cmp_gt_f32_e32 vcc, s33, v76
	v_fmamk_f32 v74, v74, 0x3a800000, v72
	v_cndmask_b32_e32 v75, v76, v77, vcc
	v_sqrt_f32_e32 v76, v75
	v_mul_f32_e32 v77, 0x4f800000, v74
	v_cmp_gt_f32_e64 s[4:5], s33, v74
	v_add_u32_e32 v78, -1, v76
	s_nop 0
	v_cndmask_b32_e64 v74, v74, v77, s[4:5]
	v_sqrt_f32_e32 v77, v74
	v_add_u32_e32 v79, 1, v76
	v_fma_f32 v80, -v78, v76, v75
	v_fma_f32 v81, -v79, v76, v75
	v_cmp_ge_f32_e64 s[6:7], 0, v80
	v_add_u32_e32 v80, 1, v77
	s_nop 0
	v_cndmask_b32_e64 v76, v76, v78, s[6:7]
	v_add_u32_e32 v78, -1, v77
	v_cmp_lt_f32_e64 s[6:7], 0, v81
	v_fma_f32 v81, -v80, v77, v74
	s_nop 0
	v_cndmask_b32_e64 v76, v76, v79, s[6:7]
	v_fma_f32 v79, -v78, v77, v74
	v_cmp_ge_f32_e64 s[6:7], 0, v79
	v_mul_f32_e32 v82, 0x37800000, v76
	v_cndmask_b32_e32 v76, v76, v82, vcc
	v_cndmask_b32_e64 v77, v77, v78, s[6:7]
	v_cmp_lt_f32_e64 s[6:7], 0, v81
	v_cmp_class_f32_e32 vcc, v75, v73
	s_nop 0
	v_cndmask_b32_e64 v77, v77, v80, s[6:7]
	v_cndmask_b32_e32 v75, v76, v75, vcc
	v_mul_f32_e32 v76, 0x37800000, v77
	v_div_scale_f32 v78, s[6:7], v75, v75, 1.0
	v_cndmask_b32_e64 v76, v77, v76, s[4:5]
	v_cmp_class_f32_e64 s[4:5], v74, v73
	v_rcp_f32_e32 v77, v78
	v_div_scale_f32 v79, vcc, 1.0, v75, 1.0
	v_cndmask_b32_e64 v76, v76, v74, s[4:5]
	v_div_scale_f32 v80, s[4:5], v76, v76, 1.0
	v_rcp_f32_e32 v82, v80
	v_fma_f32 v74, -v78, v77, 1.0
	v_fmac_f32_e32 v77, v74, v77
	v_mul_f32_e32 v74, v79, v77
	v_fma_f32 v83, -v80, v82, 1.0
	v_div_scale_f32 v81, s[4:5], 1.0, v76, 1.0
	v_fma_f32 v84, -v78, v74, v79
	v_fmac_f32_e32 v82, v83, v82
	v_fmac_f32_e32 v74, v84, v77
	v_mul_f32_e32 v83, v81, v82
	v_fma_f32 v78, -v78, v74, v79
	v_fma_f32 v79, -v80, v83, v81
	v_div_fmas_f32 v74, v78, v77, v74
	v_fmac_f32_e32 v83, v79, v82
	v_div_fixup_f32 v74, v74, v75, 1.0
	v_fma_f32 v75, -v80, v83, v81
	s_mov_b64 vcc, s[4:5]
	v_div_fmas_f32 v75, v75, v82, v83
	v_pk_mul_f32 v[62:63], v[74:75], v[62:63] op_sel_hi:[0,1]
	v_pk_mul_f32 v[64:65], v[74:75], v[64:65] op_sel_hi:[0,1]
	v_pk_mul_f32 v[58:59], v[74:75], v[58:59] op_sel_hi:[0,1]
	v_pk_mul_f32 v[60:61], v[74:75], v[60:61] op_sel_hi:[0,1]
	v_pk_mul_f32 v[50:51], v[74:75], v[50:51] op_sel_hi:[0,1]
	v_pk_mul_f32 v[52:53], v[74:75], v[52:53] op_sel_hi:[0,1]
	v_pk_mul_f32 v[54:55], v[74:75], v[54:55] op_sel_hi:[0,1]
	v_pk_mul_f32 v[56:57], v[74:75], v[56:57] op_sel_hi:[0,1]
	v_div_fixup_f32 v74, v75, v76, 1.0
	v_pk_fma_f32 v[64:65], v[4:5], v[64:65], v[8:9]
	v_pk_fma_f32 v[62:63], v[2:3], v[62:63], v[6:7]
	v_pk_fma_f32 v[52:53], v[20:21], v[52:53], v[24:25]
	v_pk_fma_f32 v[50:51], v[18:19], v[50:51], v[22:23]
	v_pk_fma_f32 v[56:57], v[28:29], v[56:57], v[32:33]
	v_pk_fma_f32 v[54:55], v[26:27], v[54:55], v[30:31]
	v_pk_mul_f32 v[46:47], v[74:75], v[46:47] op_sel_hi:[0,1]
	v_pk_mul_f32 v[48:49], v[74:75], v[48:49] op_sel_hi:[0,1]
	v_bfe_u32 v75, v62, 16, 1
	v_bfe_u32 v77, v64, 16, 1
	v_pk_fma_f32 v[60:61], v[12:13], v[60:61], v[16:17]
	v_bfe_u32 v76, v63, 16, 1
	v_bfe_u32 v78, v65, 16, 1
	v_pk_mul_f32 v[42:43], v[74:75], v[42:43] op_sel_hi:[0,1]
	v_pk_mul_f32 v[44:45], v[74:75], v[44:45] op_sel_hi:[0,1]
	v_pk_mul_f32 v[38:39], v[74:75], v[38:39] op_sel_hi:[0,1]
	v_pk_mul_f32 v[40:41], v[74:75], v[40:41] op_sel_hi:[0,1]
	v_bfe_u32 v83, v50, 16, 1
	v_bfe_u32 v84, v51, 16, 1
	v_bfe_u32 v85, v52, 16, 1
	v_bfe_u32 v86, v53, 16, 1
	v_pk_mul_f32 v[34:35], v[74:75], v[34:35] op_sel_hi:[0,1]
	v_pk_mul_f32 v[36:37], v[74:75], v[36:37] op_sel_hi:[0,1]
	v_bfe_u32 v74, v54, 16, 1
	v_bfe_u32 v87, v55, 16, 1
	v_bfe_u32 v88, v56, 16, 1
	v_bfe_u32 v89, v57, 16, 1
	v_add3_u32 v62, v62, v75, s12
	v_add3_u32 v64, v64, v77, s12
	v_bfe_u32 v82, v61, 16, 1
	v_add3_u32 v63, v63, v76, s12
	v_add3_u32 v65, v65, v78, s12
	v_add3_u32 v50, v50, v83, s12
	v_add3_u32 v75, v51, v84, s12
	v_add3_u32 v51, v52, v85, s12
	v_add3_u32 v52, v53, v86, s12
	v_add3_u32 v53, v54, v74, s12
	v_add3_u32 v54, v55, v87, s12
	v_add3_u32 v55, v56, v88, s12
	v_add3_u32 v56, v57, v89, s12
	v_lshrrev_b32_e32 v57, 16, v62
	v_lshrrev_b32_e32 v62, 16, v64
	v_add3_u32 v61, v61, v82, s12
	v_lshrrev_b32_e32 v82, 16, v50
	v_lshrrev_b32_e32 v83, 16, v51
	v_and_or_b32 v50, v63, s38, v57
	v_and_or_b32 v51, v65, s38, v62
	global_store_dwordx2 v[70:71], v[50:51], off
	s_load_dwordx2 s[4:5], s[18:19], 0x80
	v_pk_fma_f32 v[58:59], v[10:11], v[58:59], v[14:15]
	v_pk_fma_f32 v[48:49], v[4:5], v[48:49], v[8:9]
	v_bfe_u32 v79, v58, 16, 1
	v_bfe_u32 v80, v59, 16, 1
	v_pk_fma_f32 v[46:47], v[2:3], v[46:47], v[6:7]
	v_pk_fma_f32 v[42:43], v[10:11], v[42:43], v[14:15]
	v_add3_u32 v58, v58, v79, s12
	v_bfe_u32 v81, v60, 16, 1
	v_add3_u32 v59, v59, v80, s12
	v_pk_fma_f32 v[38:39], v[18:19], v[38:39], v[22:23]
	v_pk_fma_f32 v[36:37], v[28:29], v[36:37], v[32:33]
	v_pk_fma_f32 v[34:35], v[26:27], v[34:35], v[30:31]
	v_bfe_u32 v64, v46, 16, 1
	v_bfe_u32 v76, v48, 16, 1
	v_lshrrev_b32_e32 v58, 16, v58
	v_bfe_u32 v78, v42, 16, 1
	v_add3_u32 v60, v60, v81, s12
	v_bfe_u32 v74, v47, 16, 1
	v_bfe_u32 v77, v49, 16, 1
	v_bfe_u32 v79, v43, 16, 1
	v_bfe_u32 v84, v38, 16, 1
	v_lshrrev_b32_e32 v53, 16, v53
	v_bfe_u32 v88, v34, 16, 1
	v_bfe_u32 v89, v35, 16, 1
	v_bfe_u32 v90, v36, 16, 1
	v_bfe_u32 v91, v37, 16, 1
	v_add3_u32 v57, v46, v64, s12
	v_add3_u32 v48, v48, v76, s12
	v_and_or_b32 v46, v59, s38, v58
	v_add3_u32 v58, v42, v78, s12
	s_waitcnt lgkmcnt(0)
	s_add_u32 s4, s4, s36
	v_lshrrev_b32_e32 v60, 16, v60
	v_bfe_u32 v85, v39, 16, 1
	v_lshrrev_b32_e32 v55, 16, v55
	v_add3_u32 v62, v47, v74, s12
	v_add3_u32 v49, v49, v77, s12
	v_add3_u32 v59, v43, v79, s12
	v_and_or_b32 v43, v52, s38, v83
	v_add3_u32 v52, v38, v84, s12
	v_and_or_b32 v38, v54, s38, v53
	v_add3_u32 v34, v34, v88, s12
	v_add3_u32 v53, v35, v89, s12
	v_add3_u32 v35, v36, v90, s12
	v_add3_u32 v54, v37, v91, s12
	v_lshrrev_b32_e32 v36, 16, v57
	v_lshrrev_b32_e32 v37, 16, v48
	v_lshrrev_b32_e32 v48, 16, v58
	s_addc_u32 s5, s5, s37
	v_and_or_b32 v47, v61, s38, v60
	v_add3_u32 v60, v39, v85, s12
	v_and_or_b32 v39, v56, s38, v55
	v_lshrrev_b32_e32 v50, 16, v52
	v_lshrrev_b32_e32 v52, 16, v34
	v_lshrrev_b32_e32 v55, 16, v35
	v_and_or_b32 v34, v62, s38, v36
	v_and_or_b32 v35, v49, s38, v37
	v_and_or_b32 v36, v59, s38, v48
	v_lshl_add_u64 v[48:49], s[4:5], 0, v[68:69]
	v_add_co_u32_e32 v48, vcc, s39, v48
	v_pk_fma_f32 v[44:45], v[12:13], v[44:45], v[16:17]
	s_nop 0
	v_addc_co_u32_e32 v49, vcc, 0, v49, vcc
	global_store_dwordx2 v[48:49], v[34:35], off
	s_load_dwordx2 s[4:5], s[20:21], 0x80
	v_bfe_u32 v80, v44, 16, 1
	v_bfe_u32 v81, v45, 16, 1
	v_add3_u32 v44, v44, v80, s12
	v_add3_u32 v45, v45, v81, s12
	s_waitcnt lgkmcnt(0)
	s_add_u32 s4, s4, s34
	s_addc_u32 s5, s5, s35
	v_lshl_add_u64 v[34:35], s[4:5], 0, v[68:69]
	v_add_co_u32_e32 v34, vcc, s39, v34
	v_lshrrev_b32_e32 v44, 16, v44
	s_nop 0
	v_addc_co_u32_e32 v35, vcc, 0, v35, vcc
	global_store_dwordx2 v[34:35], v[46:47], off offset:512
	s_load_dwordx2 s[4:5], s[22:23], 0x80
	v_and_or_b32 v37, v45, s38, v44
	v_and_or_b32 v42, v75, s38, v82
	v_pk_fma_f32 v[40:41], v[20:21], v[40:41], v[24:25]
	v_and_or_b32 v44, v53, s38, v52
	s_waitcnt lgkmcnt(0)
	s_add_u32 s4, s4, s36
	s_addc_u32 s5, s5, s37
	v_lshl_add_u64 v[34:35], s[4:5], 0, v[68:69]
	v_add_co_u32_e32 v34, vcc, s39, v34
	v_bfe_u32 v86, v40, 16, 1
	s_nop 0
	v_addc_co_u32_e32 v35, vcc, 0, v35, vcc
	global_store_dwordx2 v[34:35], v[36:37], off offset:512
	s_load_dwordx2 s[4:5], s[24:25], 0x80
	v_bfe_u32 v87, v41, 16, 1
	v_add3_u32 v40, v40, v86, s12
	v_add3_u32 v41, v41, v87, s12
	v_lshrrev_b32_e32 v51, 16, v40
	s_waitcnt lgkmcnt(0)
	s_add_u32 s4, s4, s34
	s_addc_u32 s5, s5, s35
	v_lshl_add_u64 v[34:35], s[4:5], 0, v[68:69]
	v_add_co_u32_e32 v34, vcc, s39, v34
	v_and_or_b32 v40, v60, s38, v50
	s_nop 0
	v_addc_co_u32_e32 v35, vcc, 0, v35, vcc
	global_store_dwordx2 v[34:35], v[42:43], off offset:1024
	s_load_dwordx2 s[4:5], s[26:27], 0x80
	v_and_or_b32 v41, v41, s38, v51
	v_and_or_b32 v45, v54, s38, v55
	s_waitcnt lgkmcnt(0)
	s_add_u32 s4, s4, s36
	s_addc_u32 s5, s5, s37
	v_lshl_add_u64 v[34:35], s[4:5], 0, v[68:69]
	v_add_co_u32_e32 v34, vcc, s39, v34
	s_nop 1
	v_addc_co_u32_e32 v35, vcc, 0, v35, vcc
	global_store_dwordx2 v[34:35], v[40:41], off offset:1024
	s_load_dwordx2 s[4:5], s[28:29], 0x80
	s_waitcnt lgkmcnt(0)
	s_add_u32 s4, s4, s34
	s_addc_u32 s5, s5, s35
	v_lshl_add_u64 v[34:35], s[4:5], 0, v[68:69]
	v_add_co_u32_e32 v34, vcc, s39, v34
	s_nop 1
	v_addc_co_u32_e32 v35, vcc, 0, v35, vcc
	global_store_dwordx2 v[34:35], v[38:39], off offset:1536
	s_load_dwordx2 s[4:5], s[30:31], 0x80
	s_waitcnt lgkmcnt(0)
	s_add_u32 s4, s4, s36
	s_addc_u32 s5, s5, s37
	v_lshl_add_u64 v[34:35], s[4:5], 0, v[68:69]
	s_addk_i32 s13, 0x1000
	s_add_i32 s14, s14, 0x400000
	v_add_co_u32_e32 v34, vcc, 0x7200000, v34
	s_cmpk_gt_u32 s13, 0x6fff
	s_nop 0
	v_addc_co_u32_e32 v35, vcc, 0, v35, vcc
	global_store_dwordx2 v[34:35], v[44:45], off offset:1536
	s_cbranch_scc0 .LBB0_81
